# attention unit end: the row owner divides once and publishes lambda/l; the 16 per-lane IEEE divisions become moves
# speedup vs baseline: 1.0089x; 1.0002x over previous
.LBB0_299:
	ds_bpermute_b32 v64, v166, v174
	s_and_saveexec_b64 s[0:1], s[38:39]
	s_cbranch_execz .LBB0_301
	s_waitcnt lgkmcnt(0)
	v_add_f32_e32 v64, v174, v64
	s_cmp_eq_u32 s67, 1
	s_cselect_b64 vcc, -1, 0
	v_cndmask_b32_e32 v71, 1.0, v167, vcc
	v_div_scale_f32 v68, s[34:35], v64, v64, v71
	v_rcp_f32_e32 v70, v68
	s_nop 0
	v_fma_f32 v72, -v68, v70, 1.0
	v_fmac_f32_e32 v70, v72, v70
	v_div_scale_f32 v72, vcc, v71, v64, v71
	v_mul_f32_e32 v73, v72, v70
	v_fma_f32 v74, -v68, v73, v72
	v_fmac_f32_e32 v73, v74, v70
	v_fma_f32 v68, -v68, v73, v72
	v_div_fmas_f32 v68, v68, v70, v73
	v_div_fixup_f32 v64, v68, v64, v71
	ds_write_b32 v173, v64
.LBB0_301:
	s_or_b64 exec, exec, s[0:1]
	s_waitcnt lgkmcnt(0)
	v_add_u32_e32 v69, s66, v172
	s_waitcnt lgkmcnt(0)
	ds_read_b128 v[64:67], v69
	ds_read_b128 v[76:79], v69 offset:32
	s_waitcnt lgkmcnt(1)
	ds_read_b128 v[80:83], v69 offset:64
	s_lshl_b32 s0, s64, 14
	s_add_i32 s0, s0, 0
	v_mul_f32_e32 v72, v48, v64
	v_mul_f32_e32 v68, v32, v64
	v_mul_f32_e32 v16, v16, v64
	v_mul_f32_e32 v64, v0, v64
	v_mov_b32_e32 v48, v65
	v_mul_f32_e32 v32, v17, v48
	v_mul_f32_e32 v17, v1, v48
	v_mul_f32_e32 v0, v49, v48
	v_mul_f32_e32 v49, v33, v48
	v_mov_b32_e32 v33, v66
	v_mul_f32_e32 v73, v50, v33
	v_mul_f32_e32 v1, v34, v33
	v_mul_f32_e32 v48, v18, v33
	v_mul_f32_e32 v33, v2, v33
	v_mov_b32_e32 v34, v67
	v_mul_f32_e32 v74, v51, v34
	s_waitcnt lgkmcnt(1)
	v_mul_f32_e32 v50, v3, v34
	v_mul_f32_e32 v2, v19, v34
	v_mul_f32_e32 v18, v35, v34
	v_mov_b32_e32 v35, v76
	v_mul_f32_e32 v3, v52, v35
	v_mul_f32_e32 v19, v20, v35
	v_mul_f32_e32 v34, v36, v35
	v_mul_f32_e32 v4, v4, v35
	v_mov_b32_e32 v20, v77
	v_mul_f32_e32 v36, v53, v20
	v_mul_f32_e32 v53, v21, v20
	v_mul_f32_e32 v21, v5, v20
	v_mul_f32_e32 v51, v37, v20
	v_mov_b32_e32 v37, v78
	v_mul_f32_e32 v20, v54, v37
	v_mul_f32_e32 v5, v38, v37
	v_mul_f32_e32 v35, v22, v37
	v_mul_f32_e32 v37, v6, v37
	v_mov_b32_e32 v38, v79
	ds_read_b128 v[76:79], v69 offset:96
	s_waitcnt lgkmcnt(1)
	v_mul_f32_e32 v65, v7, v38
	v_mul_f32_e32 v69, v23, v38
	v_mul_f32_e32 v6, v55, v38
	v_mul_f32_e32 v22, v39, v38
	v_mov_b32_e32 v38, v80
	v_mul_f32_e32 v7, v24, v38
	v_mul_f32_e32 v23, v56, v38
	v_mul_f32_e32 v40, v40, v38
	v_mul_f32_e32 v8, v8, v38
	v_mov_b32_e32 v39, v81
	v_mul_f32_e32 v24, v25, v39
	v_mul_f32_e32 v38, v57, v39
	v_mul_f32_e32 v56, v41, v39
	v_mul_f32_e32 v9, v9, v39
	v_mov_b32_e32 v25, v82
	v_mul_f32_e32 v41, v58, v25
	v_mul_f32_e32 v75, v42, v25
	v_mul_f32_e32 v42, v26, v25
	v_mul_f32_e32 v25, v10, v25
	s_waitcnt lgkmcnt(0)
	v_mov_b32_e32 v39, v83
	v_mul_f32_e32 v66, v11, v39
	v_mul_f32_e32 v58, v27, v39
	v_mul_f32_e32 v26, v59, v39
	v_mul_f32_e32 v10, v43, v39
	v_mov_b32_e32 v39, v76
	v_mul_f32_e32 v67, v12, v39
	v_mul_f32_e32 v11, v28, v39
	v_mul_f32_e32 v54, v60, v39
	v_mul_f32_e32 v27, v44, v39
	v_mov_b32_e32 v12, v77
	v_mul_f32_e32 v77, v61, v12
	v_mul_f32_e32 v59, v45, v12
	v_mul_f32_e32 v29, v29, v12
	v_mul_f32_e32 v13, v13, v12
	v_mov_b32_e32 v12, v78
	v_mul_f32_e32 v57, v62, v12
	v_mul_f32_e32 v43, v46, v12
	v_mul_f32_e32 v45, v30, v12
	v_mul_f32_e32 v70, v14, v12
	v_mov_b32_e32 v12, v79
	s_cmp_lg_u32 s67, 1
	v_mul_f32_e32 v14, v63, v12
	v_mul_f32_e32 v76, v47, v12
	v_mul_f32_e32 v61, v31, v12
	v_mul_f32_e32 v63, v15, v12
	v_lshl_add_u32 v71, v168, 2, s0
	s_cbranch_scc1 .LBB0_303
	ds_write2st64_b32 v71, v72, v0 offset1:1
	ds_write2st64_b32 v71, v73, v74 offset0:2 offset1:3
	ds_write2st64_b32 v71, v3, v36 offset0:4 offset1:5
	ds_write2st64_b32 v71, v20, v6 offset0:6 offset1:7
	ds_write2st64_b32 v71, v23, v38 offset0:8 offset1:9
	ds_write2st64_b32 v71, v41, v26 offset0:10 offset1:11
	ds_write2st64_b32 v71, v54, v77 offset0:12 offset1:13
	ds_write2st64_b32 v71, v57, v14 offset0:14 offset1:15
	ds_write2st64_b32 v71, v68, v49 offset0:16 offset1:17
	ds_write2st64_b32 v71, v1, v18 offset0:18 offset1:19
	ds_write2st64_b32 v71, v34, v51 offset0:20 offset1:21
	ds_write2st64_b32 v71, v5, v22 offset0:22 offset1:23
	ds_write2st64_b32 v71, v40, v56 offset0:24 offset1:25
	ds_write2st64_b32 v71, v75, v10 offset0:26 offset1:27
	ds_write2st64_b32 v71, v27, v59 offset0:28 offset1:29
	ds_write2st64_b32 v71, v43, v76 offset0:30 offset1:31
	ds_write2st64_b32 v71, v16, v32 offset0:32 offset1:33
	ds_write2st64_b32 v71, v48, v2 offset0:34 offset1:35
	ds_write2st64_b32 v71, v19, v53 offset0:36 offset1:37
	ds_write2st64_b32 v71, v35, v69 offset0:38 offset1:39
	ds_write2st64_b32 v71, v7, v24 offset0:40 offset1:41
	ds_write2st64_b32 v71, v42, v58 offset0:42 offset1:43
	ds_write2st64_b32 v71, v11, v29 offset0:44 offset1:45
	ds_write2st64_b32 v71, v45, v61 offset0:46 offset1:47
	ds_write2st64_b32 v71, v64, v17 offset0:48 offset1:49
	ds_write2st64_b32 v71, v33, v50 offset0:50 offset1:51
	ds_write2st64_b32 v71, v4, v21 offset0:52 offset1:53
	ds_write2st64_b32 v71, v37, v65 offset0:54 offset1:55
	ds_write2st64_b32 v71, v8, v9 offset0:56 offset1:57
	ds_write2st64_b32 v71, v25, v66 offset0:58 offset1:59
	ds_write2st64_b32 v71, v67, v13 offset0:60 offset1:61
	ds_write2st64_b32 v71, v70, v63 offset0:62 offset1:63
